# ctx_fin<11> row loops rewritten: 30 loads in flight per wave with counted waits; rows dealt to all 256 CUs
# speedup vs baseline: 1.0400x; 1.0119x over previous
.LBB0_469:
	s_cmp_lg_u32 s50, -1
	s_cselect_b32 s0, s50, 0
	s_cselect_b32 s1, s55, 0
	s_cmp_lg_u32 s51, -1
	v_mov_b32_e32 v2, s0
	v_mov_b32_e32 v3, s1
	s_cselect_b32 s0, s51, 0
	s_cselect_b32 s1, s55, 0
	s_cmp_lg_u32 s57, -1
	flat_load_dword v4, v[2:3] sc0 sc1
	s_waitcnt vmcnt(0)
	v_mov_b32_e32 v2, s0
	v_mov_b32_e32 v3, s1
	s_cselect_b32 s0, s57, 0
	s_cselect_b32 s1, s55, 0
	s_cmp_lg_u32 s58, -1
	flat_load_dword v5, v[2:3] sc0 sc1
	s_waitcnt vmcnt(0)
	v_mov_b32_e32 v1, v224
	v_mov_b32_e32 v2, s0
	v_mov_b32_e32 v3, s1
	s_cselect_b32 s0, s58, 0
	s_cselect_b32 s1, s55, 0
	flat_load_dword v7, v[2:3] sc0 sc1
	s_waitcnt vmcnt(0)
	v_mov_b32_e32 v2, s0
	v_mov_b32_e32 v3, s1
	flat_load_dword v2, v[2:3] sc0 sc1
	s_waitcnt vmcnt(0)
	v_ashrrev_i32_e32 v3, 6, v1
	v_readlane_b32 s0, v253, 6
	s_movk_i32 s4, 0x400
	s_waitcnt lgkmcnt(0)
	v_readfirstlane_b32 s1, v5
	v_mul_lo_u32 v6, v3, s76
	v_add_u32_e32 v6, s75, v6
	v_readfirstlane_b32 s0, v4
	v_cmp_gt_i32_e32 vcc, s4, v6
	v_readfirstlane_b32 s8, v7
	v_readfirstlane_b32 s9, v2
	s_and_saveexec_b64 s[4:5], vcc
	s_cbranch_execz .LBB0_474
	v_and_b32_e32 v4, 63, v1
	v_and_b32_e32 v1, 64, v230
	v_add_u32_e32 v2, 64, v1
	v_xor_b32_e32 v1, 1, v230
	v_cmp_lt_i32_e32 vcc, v1, v2
	v_xor_b32_e32 v3, 2, v230
	v_readlane_b32 s12, v254, 36
	v_cndmask_b32_e32 v1, v230, v1, vcc
	v_cmp_lt_i32_e32 vcc, v3, v2
	v_readlane_b32 s13, v254, 37
	s_lshl_b64 s[12:13], s[12:13], 2
	v_cndmask_b32_e32 v3, v230, v3, vcc
	v_lshlrev_b32_e32 v68, 2, v3
	v_xor_b32_e32 v3, 4, v230
	v_cmp_lt_i32_e32 vcc, v3, v2
	s_add_u32 s12, s0, s12
	s_addc_u32 s13, s1, s13
	v_cndmask_b32_e32 v3, v230, v3, vcc
	v_lshlrev_b32_e32 v69, 2, v3
	v_xor_b32_e32 v3, 8, v230
	v_cmp_lt_i32_e32 vcc, v3, v2
	s_add_u32 s0, s8, s53
	s_addc_u32 s1, s9, 0
	v_cndmask_b32_e32 v3, v230, v3, vcc
	v_lshlrev_b32_e32 v70, 2, v3
	v_xor_b32_e32 v3, 16, v230
	s_add_u32 s14, s0, 0x24000
	v_cmp_lt_i32_e32 vcc, v3, v2
	s_addc_u32 s15, s1, 0
	s_add_u32 s0, s8, s52
	v_cndmask_b32_e32 v3, v230, v3, vcc
	v_lshlrev_b32_e32 v71, 2, v3
	v_xor_b32_e32 v3, 32, v230
	s_addc_u32 s1, s9, 0
	v_cmp_lt_i32_e32 vcc, v3, v2
	s_add_u32 s16, s0, 0x24000
	v_lshlrev_b32_e32 v8, 4, v4
	v_cndmask_b32_e32 v2, v230, v3, vcc
	s_addc_u32 s17, s1, 0
	v_lshlrev_b32_e32 v72, 2, v2
	v_or_b32_e32 v2, 0x400, v8
	v_mov_b32_e32 v3, v0
	v_lshl_add_u64 v[16:17], s[16:17], 0, v[2:3]
	v_lshl_add_u64 v[18:19], s[14:15], 0, v[2:3]
	v_or_b32_e32 v2, 0x800, v8
	v_lshl_add_u64 v[20:21], s[16:17], 0, v[2:3]
	v_lshl_add_u64 v[22:23], s[14:15], 0, v[2:3]
	v_or_b32_e32 v2, 0xc00, v8
	v_mov_b32_e32 v9, v0
	v_lshl_add_u64 v[24:25], s[16:17], 0, v[2:3]
	v_lshl_add_u64 v[26:27], s[14:15], 0, v[2:3]
	v_lshlrev_b32_e32 v2, 3, v4
	v_lshl_add_u64 v[12:13], s[12:13], 0, v[8:9]
	v_lshl_add_u64 v[2:3], s[8:9], 0, v[2:3]
	s_mov_b64 s[12:13], 0x5a00000
	v_lshl_add_u64 v[28:29], v[2:3], 0, s[12:13]
	v_readlane_b32 s12, v254, 28
	s_mul_hi_u32 s13, s12, 0x33000
	v_readlane_b32 s12, v254, 26
	s_add_u32 s12, s8, s12
	v_ashrrev_i32_e32 v7, 31, v6
	s_addc_u32 s13, s9, s13
	v_lshl_add_u64 v[2:3], v[6:7], 2, s[12:13]
	s_mov_b64 s[12:13], 0x1a1000
	v_lshl_add_u64 v[30:31], v[2:3], 0, s[12:13]
	v_lshlrev_b64 v[2:3], 12, v[6:7]
	v_lshlrev_b32_e32 v1, 2, v1
	v_cmp_eq_u32_e64 s[0:1], 0, v4
	v_lshl_add_u64 v[10:11], s[16:17], 0, v[8:9]
	v_lshl_add_u64 v[14:15], s[14:15], 0, v[8:9]
	v_lshl_add_u64 v[32:33], s[8:9], 0, v[2:3]
	v_lshl_add_u64 v[34:35], s[6:7], 0, v[2:3]
	s_mov_b64 s[6:7], 0
	s_branch .LBB0_472

.LBB0_472:
	s_waitcnt lgkmcnt(0)
	v_lshl_add_u64 v[56:57], v[32:33], 0, v[8:9]
	v_lshl_add_u64 v[60:61], v[34:35], 0, v[8:9]
	v_add_u32_e32 v50, 0x4000, v6
	v_ashrrev_i32_e32 v51, 31, v50
	v_lshlrev_b64 v[62:63], 11, v[50:51]
	v_lshl_add_u64 v[62:63], v[28:29], 0, v[62:63]
	s_mov_b32 s85, 0
	s_mov_b32 s84, 0x400000
	v_lshl_add_u64 v[58:59], v[56:57], 0, s[84:85]
	s_mov_b32 s84, 0xda00000
	v_lshl_add_u64 v[100:101], v[56:57], 0, s[84:85]
	s_add_u32 s84, s84, 0x400000
	v_lshl_add_u64 v[102:103], v[56:57], 0, s[84:85]
	s_add_u32 s84, s84, 0x400000
	v_lshl_add_u64 v[104:105], v[56:57], 0, s[84:85]
	s_add_u32 s84, s84, 0x400000
	v_lshl_add_u64 v[106:107], v[56:57], 0, s[84:85]
	s_add_u32 s84, s84, 0x400000
	v_lshl_add_u64 v[108:109], v[56:57], 0, s[84:85]
	s_add_u32 s84, s84, 0x400000
	v_lshl_add_u64 v[110:111], v[56:57], 0, s[84:85]
	s_add_u32 s84, s84, 0x400000
	v_lshl_add_u64 v[112:113], v[56:57], 0, s[84:85]
	s_add_u32 s84, s84, 0x400000
	v_lshl_add_u64 v[114:115], v[56:57], 0, s[84:85]
	s_add_u32 s84, s84, 0x400000
	v_lshl_add_u64 v[116:117], v[56:57], 0, s[84:85]
	s_add_u32 s84, s84, 0x400000
	v_lshl_add_u64 v[118:119], v[56:57], 0, s[84:85]
	s_add_u32 s84, s84, 0x400000
	v_lshl_add_u64 v[120:121], v[56:57], 0, s[84:85]
	global_load_dwordx4 v[148:151], v[100:101], off
	global_load_dwordx4 v[152:155], v[102:103], off
	global_load_dwordx4 v[156:159], v[104:105], off
	global_load_dwordx4 v[160:163], v[106:107], off
	global_load_dwordx4 v[164:167], v[108:109], off
	global_load_dwordx4 v[168:171], v[110:111], off
	global_load_dwordx4 v[172:175], v[112:113], off
	global_load_dwordx4 v[176:179], v[114:115], off
	global_load_dwordx4 v[180:183], v[116:117], off
	global_load_dwordx4 v[184:187], v[118:119], off
	global_load_dwordx4 v[188:191], v[120:121], off
	global_load_dwordx4 v[92:95], v[60:61], off
	global_load_dwordx4 v[42:45], v[10:11], off
	global_load_dwordx4 v[122:125], v[12:13], off
	global_load_dwordx4 v[130:133], v[14:15], off
	global_load_dwordx4 v[192:195], v[100:101], off offset:1024
	global_load_dwordx4 v[196:199], v[102:103], off offset:1024
	global_load_dwordx4 v[200:203], v[104:105], off offset:1024
	global_load_dwordx4 v[204:207], v[106:107], off offset:1024
	global_load_dwordx4 v[208:211], v[108:109], off offset:1024
	global_load_dwordx4 v[212:215], v[110:111], off offset:1024
	global_load_dwordx4 v[216:219], v[112:113], off offset:1024
	global_load_dwordx4 v[220:223], v[114:115], off offset:1024
	global_load_dwordx4 v[80:83], v[116:117], off offset:1024
	global_load_dwordx4 v[84:87], v[118:119], off offset:1024
	global_load_dwordx4 v[88:91], v[120:121], off offset:1024
	global_load_dwordx4 v[96:99], v[60:61], off offset:1024
	global_load_dwordx4 v[46:49], v[10:11], off offset:1024
	global_load_dwordx4 v[126:129], v[12:13], off offset:1024
	global_load_dwordx4 v[134:137], v[14:15], off offset:1024
	s_waitcnt vmcnt(15)
	v_pk_add_f32 v[66:67], v[150:151], 0 op_sel_hi:[1,0]
	v_pk_add_f32 v[64:65], v[148:149], 0 op_sel_hi:[1,0]
	v_pk_add_f32 v[66:67], v[66:67], v[154:155]
	v_pk_add_f32 v[64:65], v[64:65], v[152:153]
	v_pk_add_f32 v[66:67], v[66:67], v[158:159]
	v_pk_add_f32 v[64:65], v[64:65], v[156:157]
	v_pk_add_f32 v[66:67], v[66:67], v[162:163]
	v_pk_add_f32 v[64:65], v[64:65], v[160:161]
	v_pk_add_f32 v[66:67], v[66:67], v[166:167]
	v_pk_add_f32 v[64:65], v[64:65], v[164:165]
	v_pk_add_f32 v[66:67], v[66:67], v[170:171]
	v_pk_add_f32 v[64:65], v[64:65], v[168:169]
	v_pk_add_f32 v[66:67], v[66:67], v[174:175]
	v_pk_add_f32 v[64:65], v[64:65], v[172:173]
	v_pk_add_f32 v[66:67], v[66:67], v[178:179]
	v_pk_add_f32 v[64:65], v[64:65], v[176:177]
	v_pk_add_f32 v[66:67], v[66:67], v[182:183]
	v_pk_add_f32 v[64:65], v[64:65], v[180:181]
	v_pk_add_f32 v[66:67], v[66:67], v[186:187]
	v_pk_add_f32 v[64:65], v[64:65], v[184:185]
	v_pk_add_f32 v[66:67], v[66:67], v[190:191]
	v_pk_add_f32 v[64:65], v[64:65], v[188:189]
	v_pk_mul_f32 v[44:45], v[44:45], 0.5 op_sel_hi:[1,0]
	v_pk_mul_f32 v[42:43], v[42:43], 0.5 op_sel_hi:[1,0]
	v_pk_fma_f32 v[4:5], v[66:67], v[44:45], v[94:95]
	v_pk_fma_f32 v[2:3], v[64:65], v[42:43], v[92:93]
	v_mul_f32_e32 v138, v5, v5
	v_mul_f32_e32 v7, v3, v3
	global_store_dwordx4 v[58:59], v[2:5], off
	v_fmac_f32_e32 v7, v2, v2
	v_fmac_f32_e32 v138, v4, v4
	v_add_f32_e32 v7, v7, v138
	v_pk_add_f32 v[132:133], v[132:133], 1.0 op_sel_hi:[1,0]
	v_pk_add_f32 v[130:131], v[130:131], 1.0 op_sel_hi:[1,0]
	v_pk_mul_f32 v[124:125], v[124:125], v[132:133]
	v_pk_mul_f32 v[122:123], v[122:123], v[130:131]
	v_pk_mul_f32 v[142:143], v[4:5], v[124:125]
	v_pk_mul_f32 v[140:141], v[2:3], v[122:123]
	s_nop 0
	v_cvt_pk_bf16_f32 v140, v140, v141
	v_cvt_pk_bf16_f32 v141, v142, v143
	global_store_dwordx2 v[62:63], v[140:141], off
	s_waitcnt vmcnt(2)
	v_pk_add_f32 v[66:67], v[194:195], 0 op_sel_hi:[1,0]
	v_pk_add_f32 v[64:65], v[192:193], 0 op_sel_hi:[1,0]
	v_pk_add_f32 v[66:67], v[66:67], v[198:199]
	v_pk_add_f32 v[64:65], v[64:65], v[196:197]
	v_pk_add_f32 v[66:67], v[66:67], v[202:203]
	v_pk_add_f32 v[64:65], v[64:65], v[200:201]
	v_pk_add_f32 v[66:67], v[66:67], v[206:207]
	v_pk_add_f32 v[64:65], v[64:65], v[204:205]
	v_pk_add_f32 v[66:67], v[66:67], v[210:211]
	v_pk_add_f32 v[64:65], v[64:65], v[208:209]
	v_pk_add_f32 v[66:67], v[66:67], v[214:215]
	v_pk_add_f32 v[64:65], v[64:65], v[212:213]
	v_pk_add_f32 v[66:67], v[66:67], v[218:219]
	v_pk_add_f32 v[64:65], v[64:65], v[216:217]
	v_pk_add_f32 v[66:67], v[66:67], v[222:223]
	v_pk_add_f32 v[64:65], v[64:65], v[220:221]
	v_pk_add_f32 v[66:67], v[66:67], v[82:83]
	v_pk_add_f32 v[64:65], v[64:65], v[80:81]
	v_pk_add_f32 v[66:67], v[66:67], v[86:87]
	v_pk_add_f32 v[64:65], v[64:65], v[84:85]
	v_pk_add_f32 v[66:67], v[66:67], v[90:91]
	v_pk_add_f32 v[64:65], v[64:65], v[88:89]
	v_pk_mul_f32 v[48:49], v[48:49], 0.5 op_sel_hi:[1,0]
	v_pk_mul_f32 v[46:47], v[46:47], 0.5 op_sel_hi:[1,0]
	v_pk_fma_f32 v[4:5], v[66:67], v[48:49], v[98:99]
	v_pk_fma_f32 v[2:3], v[64:65], v[46:47], v[96:97]
	v_mul_f32_e32 v139, v5, v5
	v_mul_f32_e32 v138, v3, v3
	v_fmac_f32_e32 v138, v2, v2
	v_fmac_f32_e32 v139, v4, v4
	global_store_dwordx4 v[58:59], v[2:5], off offset:1024
	v_add_f32_e32 v138, v138, v139
	v_add_f32_e32 v7, v7, v138
	v_pk_add_f32 v[136:137], v[136:137], 1.0 op_sel_hi:[1,0]
	v_pk_add_f32 v[134:135], v[134:135], 1.0 op_sel_hi:[1,0]
	v_pk_mul_f32 v[128:129], v[128:129], v[136:137]
	v_pk_mul_f32 v[126:127], v[126:127], v[134:135]
	v_pk_mul_f32 v[142:143], v[4:5], v[128:129]
	v_pk_mul_f32 v[140:141], v[2:3], v[126:127]
	s_nop 0
	v_cvt_pk_bf16_f32 v140, v140, v141
	v_cvt_pk_bf16_f32 v141, v142, v143
	global_store_dwordx2 v[62:63], v[140:141], off offset:512
	global_load_dwordx4 v[148:151], v[100:101], off offset:2048
	global_load_dwordx4 v[152:155], v[102:103], off offset:2048
	global_load_dwordx4 v[156:159], v[104:105], off offset:2048
	global_load_dwordx4 v[160:163], v[106:107], off offset:2048
	global_load_dwordx4 v[164:167], v[108:109], off offset:2048
	global_load_dwordx4 v[168:171], v[110:111], off offset:2048
	global_load_dwordx4 v[172:175], v[112:113], off offset:2048
	global_load_dwordx4 v[176:179], v[114:115], off offset:2048
	global_load_dwordx4 v[180:183], v[116:117], off offset:2048
	global_load_dwordx4 v[184:187], v[118:119], off offset:2048
	global_load_dwordx4 v[188:191], v[120:121], off offset:2048
	global_load_dwordx4 v[92:95], v[60:61], off offset:2048
	global_load_dwordx4 v[42:45], v[10:11], off offset:2048
	global_load_dwordx4 v[122:125], v[12:13], off offset:2048
	global_load_dwordx4 v[130:133], v[14:15], off offset:2048
	global_load_dwordx4 v[192:195], v[100:101], off offset:3072
	global_load_dwordx4 v[196:199], v[102:103], off offset:3072
	global_load_dwordx4 v[200:203], v[104:105], off offset:3072
	global_load_dwordx4 v[204:207], v[106:107], off offset:3072
	global_load_dwordx4 v[208:211], v[108:109], off offset:3072
	global_load_dwordx4 v[212:215], v[110:111], off offset:3072
	global_load_dwordx4 v[216:219], v[112:113], off offset:3072
	global_load_dwordx4 v[220:223], v[114:115], off offset:3072
	global_load_dwordx4 v[80:83], v[116:117], off offset:3072
	global_load_dwordx4 v[84:87], v[118:119], off offset:3072
	global_load_dwordx4 v[88:91], v[120:121], off offset:3072
	global_load_dwordx4 v[96:99], v[60:61], off offset:3072
	global_load_dwordx4 v[46:49], v[10:11], off offset:3072
	global_load_dwordx4 v[126:129], v[12:13], off offset:3072
	global_load_dwordx4 v[134:137], v[14:15], off offset:3072
	s_waitcnt vmcnt(15)
	v_pk_add_f32 v[66:67], v[150:151], 0 op_sel_hi:[1,0]
	v_pk_add_f32 v[64:65], v[148:149], 0 op_sel_hi:[1,0]
	v_pk_add_f32 v[66:67], v[66:67], v[154:155]
	v_pk_add_f32 v[64:65], v[64:65], v[152:153]
	v_pk_add_f32 v[66:67], v[66:67], v[158:159]
	v_pk_add_f32 v[64:65], v[64:65], v[156:157]
	v_pk_add_f32 v[66:67], v[66:67], v[162:163]
	v_pk_add_f32 v[64:65], v[64:65], v[160:161]
	v_pk_add_f32 v[66:67], v[66:67], v[166:167]
	v_pk_add_f32 v[64:65], v[64:65], v[164:165]
	v_pk_add_f32 v[66:67], v[66:67], v[170:171]
	v_pk_add_f32 v[64:65], v[64:65], v[168:169]
	v_pk_add_f32 v[66:67], v[66:67], v[174:175]
	v_pk_add_f32 v[64:65], v[64:65], v[172:173]
	v_pk_add_f32 v[66:67], v[66:67], v[178:179]
	v_pk_add_f32 v[64:65], v[64:65], v[176:177]
	v_pk_add_f32 v[66:67], v[66:67], v[182:183]
	v_pk_add_f32 v[64:65], v[64:65], v[180:181]
	v_pk_add_f32 v[66:67], v[66:67], v[186:187]
	v_pk_add_f32 v[64:65], v[64:65], v[184:185]
	v_pk_add_f32 v[66:67], v[66:67], v[190:191]
	v_pk_add_f32 v[64:65], v[64:65], v[188:189]
	v_pk_mul_f32 v[44:45], v[44:45], 0.5 op_sel_hi:[1,0]
	v_pk_mul_f32 v[42:43], v[42:43], 0.5 op_sel_hi:[1,0]
	v_pk_fma_f32 v[4:5], v[66:67], v[44:45], v[94:95]
	v_pk_fma_f32 v[2:3], v[64:65], v[42:43], v[92:93]
	v_mul_f32_e32 v139, v5, v5
	v_mul_f32_e32 v138, v3, v3
	v_fmac_f32_e32 v138, v2, v2
	v_fmac_f32_e32 v139, v4, v4
	global_store_dwordx4 v[58:59], v[2:5], off offset:2048
	v_add_f32_e32 v138, v138, v139
	v_add_f32_e32 v7, v7, v138
	v_pk_add_f32 v[132:133], v[132:133], 1.0 op_sel_hi:[1,0]
	v_pk_add_f32 v[130:131], v[130:131], 1.0 op_sel_hi:[1,0]
	v_pk_mul_f32 v[124:125], v[124:125], v[132:133]
	v_pk_mul_f32 v[122:123], v[122:123], v[130:131]
	v_pk_mul_f32 v[142:143], v[4:5], v[124:125]
	v_pk_mul_f32 v[140:141], v[2:3], v[122:123]
	s_nop 0
	v_cvt_pk_bf16_f32 v140, v140, v141
	v_cvt_pk_bf16_f32 v141, v142, v143
	global_store_dwordx2 v[62:63], v[140:141], off offset:1024
	s_waitcnt vmcnt(2)
	v_pk_add_f32 v[66:67], v[194:195], 0 op_sel_hi:[1,0]
	v_pk_add_f32 v[64:65], v[192:193], 0 op_sel_hi:[1,0]
	v_pk_add_f32 v[66:67], v[66:67], v[198:199]
	v_pk_add_f32 v[64:65], v[64:65], v[196:197]
	v_pk_add_f32 v[66:67], v[66:67], v[202:203]
	v_pk_add_f32 v[64:65], v[64:65], v[200:201]
	v_pk_add_f32 v[66:67], v[66:67], v[206:207]
	v_pk_add_f32 v[64:65], v[64:65], v[204:205]
	v_pk_add_f32 v[66:67], v[66:67], v[210:211]
	v_pk_add_f32 v[64:65], v[64:65], v[208:209]
	v_pk_add_f32 v[66:67], v[66:67], v[214:215]
	v_pk_add_f32 v[64:65], v[64:65], v[212:213]
	v_pk_add_f32 v[66:67], v[66:67], v[218:219]
	v_pk_add_f32 v[64:65], v[64:65], v[216:217]
	v_pk_add_f32 v[66:67], v[66:67], v[222:223]
	v_pk_add_f32 v[64:65], v[64:65], v[220:221]
	v_pk_add_f32 v[66:67], v[66:67], v[82:83]
	v_pk_add_f32 v[64:65], v[64:65], v[80:81]
	v_pk_add_f32 v[66:67], v[66:67], v[86:87]
	v_pk_add_f32 v[64:65], v[64:65], v[84:85]
	v_pk_add_f32 v[66:67], v[66:67], v[90:91]
	v_pk_add_f32 v[64:65], v[64:65], v[88:89]
	v_pk_mul_f32 v[48:49], v[48:49], 0.5 op_sel_hi:[1,0]
	v_pk_mul_f32 v[46:47], v[46:47], 0.5 op_sel_hi:[1,0]
	v_pk_fma_f32 v[4:5], v[66:67], v[48:49], v[98:99]
	v_pk_fma_f32 v[2:3], v[64:65], v[46:47], v[96:97]
	v_mul_f32_e32 v139, v5, v5
	v_mul_f32_e32 v138, v3, v3
	v_fmac_f32_e32 v138, v2, v2
	v_fmac_f32_e32 v139, v4, v4
	global_store_dwordx4 v[58:59], v[2:5], off offset:3072
	v_add_f32_e32 v138, v138, v139
	v_add_f32_e32 v7, v7, v138
	v_pk_add_f32 v[136:137], v[136:137], 1.0 op_sel_hi:[1,0]
	v_pk_add_f32 v[134:135], v[134:135], 1.0 op_sel_hi:[1,0]
	v_pk_mul_f32 v[128:129], v[128:129], v[136:137]
	v_pk_mul_f32 v[126:127], v[126:127], v[134:135]
	v_pk_mul_f32 v[142:143], v[4:5], v[128:129]
	v_pk_mul_f32 v[140:141], v[2:3], v[126:127]
	s_nop 0
	v_cvt_pk_bf16_f32 v140, v140, v141
	v_cvt_pk_bf16_f32 v141, v142, v143
	global_store_dwordx2 v[62:63], v[140:141], off offset:1536
	ds_bpermute_b32 v2, v1, v7
	s_waitcnt lgkmcnt(0)
	v_add_f32_e32 v2, v7, v2
	ds_bpermute_b32 v3, v68, v2
	s_waitcnt lgkmcnt(0)
	v_add_f32_e32 v2, v2, v3
	ds_bpermute_b32 v3, v69, v2
	s_waitcnt lgkmcnt(0)
	v_add_f32_e32 v2, v2, v3
	ds_bpermute_b32 v3, v70, v2
	s_waitcnt lgkmcnt(0)
	v_add_f32_e32 v2, v2, v3
	ds_bpermute_b32 v3, v71, v2
	s_waitcnt lgkmcnt(0)
	v_add_f32_e32 v2, v2, v3
	ds_bpermute_b32 v3, v72, v2
	s_and_saveexec_b64 s[8:9], s[0:1]
	s_cbranch_execz .LBB0_471
	s_waitcnt lgkmcnt(0)
	v_add_f32_e32 v2, v2, v3
	global_store_dword v[30:31], v2, off
	s_branch .LBB0_471

.LBB0_1724:
	s_cmp_lg_u32 s57, -1
	s_cselect_b32 s0, s57, 0
	s_cselect_b32 s1, s55, 0
	s_cmp_lg_u32 s58, -1
	v_mov_b64_e32 v[2:3], s[0:1]
	s_cselect_b32 s0, s58, 0
	s_cselect_b32 s1, s55, 0
	v_mov_b64_e32 v[4:5], s[0:1]
	flat_load_dword v1, v[2:3] sc0 sc1
	s_waitcnt vmcnt(0)
	flat_load_dword v6, v[4:5] sc0 sc1
	s_waitcnt vmcnt(0)
	v_readlane_b32 s0, v253, 4
	s_cmp_lg_u32 s0, -1
	s_cselect_b32 s0, s0, 0
	s_cselect_b32 s1, s55, 0
	v_mov_b32_e32 v7, s1
	v_readlane_b32 s4, v253, 6
	s_waitcnt lgkmcnt(0)
	v_readfirstlane_b32 s6, v1
	v_readfirstlane_b32 s7, v6
	v_mov_b32_e32 v6, s0
	flat_load_dword v1, v[6:7] sc0 sc1
	s_waitcnt vmcnt(0)
	v_readlane_b32 s0, v253, 5
	s_cmp_lg_u32 s0, -1
	s_cselect_b32 s0, s0, 0
	s_cselect_b32 s1, s55, 0
	v_mov_b32_e32 v6, s0
	v_mov_b32_e32 v7, s1
	flat_load_dword v6, v[6:7] sc0 sc1
	s_waitcnt vmcnt(0) lgkmcnt(0)
	v_readfirstlane_b32 s0, v1
	v_mov_b32_e32 v1, v224
	flat_load_dword v2, v[2:3] sc0 sc1
	s_waitcnt vmcnt(0)
	flat_load_dword v3, v[4:5] sc0 sc1
	s_waitcnt vmcnt(0)
	v_readfirstlane_b32 s1, v6
	v_ashrrev_i32_e32 v6, 6, v1
	v_mul_lo_u32 v6, v6, s76
	v_add_u32_e32 v6, s75, v6
	s_movk_i32 s4, 0x400
	v_cmp_gt_i32_e32 vcc, s4, v6
	s_waitcnt lgkmcnt(0)
	v_readfirstlane_b32 s8, v2
	v_readfirstlane_b32 s9, v3
	s_and_saveexec_b64 s[4:5], vcc
	s_cbranch_execz .LBB0_1729
	v_and_b32_e32 v4, 63, v1
	v_and_b32_e32 v1, 64, v230
	v_add_u32_e32 v2, 64, v1
	v_xor_b32_e32 v1, 1, v230
	v_cmp_lt_i32_e32 vcc, v1, v2
	v_xor_b32_e32 v3, 2, v230
	s_add_u32 s10, s0, 0x1000
	v_cndmask_b32_e32 v1, v230, v1, vcc
	v_cmp_lt_i32_e32 vcc, v3, v2
	s_addc_u32 s11, s1, 0
	s_add_u32 s12, s8, 0x52000
	v_cndmask_b32_e32 v3, v230, v3, vcc
	v_lshlrev_b32_e32 v74, 2, v3
	v_xor_b32_e32 v3, 4, v230
	v_cmp_lt_i32_e32 vcc, v3, v2
	s_addc_u32 s13, s9, 0
	s_add_u32 s0, s8, s48
	v_cndmask_b32_e32 v3, v230, v3, vcc
	v_lshlrev_b32_e32 v75, 2, v3
	v_xor_b32_e32 v3, 8, v230
	v_cmp_lt_i32_e32 vcc, v3, v2
	s_addc_u32 s1, s9, 0
	s_add_u32 s14, s0, 0x24000
	v_cndmask_b32_e32 v3, v230, v3, vcc
	v_lshlrev_b32_e32 v76, 2, v3
	v_xor_b32_e32 v3, 16, v230
	v_cmp_lt_i32_e32 vcc, v3, v2
	v_lshlrev_b32_e32 v8, 4, v4
	s_addc_u32 s15, s1, 0
	v_cndmask_b32_e32 v3, v230, v3, vcc
	v_lshlrev_b32_e32 v77, 2, v3
	v_xor_b32_e32 v3, 32, v230
	v_cmp_lt_i32_e32 vcc, v3, v2
	v_mov_b32_e32 v9, v0
	v_lshl_add_u64 v[12:13], s[10:11], 0, v[8:9]
	v_cndmask_b32_e32 v2, v230, v3, vcc
	v_lshlrev_b32_e32 v78, 2, v2
	v_or_b32_e32 v2, 0x400, v8
	v_mov_b32_e32 v3, v0
	v_lshl_add_u64 v[16:17], s[14:15], 0, v[2:3]
	v_lshl_add_u64 v[18:19], s[10:11], 0, v[2:3]
	v_lshl_add_u64 v[20:21], s[12:13], 0, v[2:3]
	v_or_b32_e32 v2, 0x800, v8
	v_lshl_add_u64 v[22:23], s[14:15], 0, v[2:3]
	v_lshl_add_u64 v[24:25], s[10:11], 0, v[2:3]
	v_lshl_add_u64 v[26:27], s[12:13], 0, v[2:3]
	v_or_b32_e32 v2, 0xc00, v8
	v_lshl_add_u64 v[28:29], s[14:15], 0, v[2:3]
	v_lshl_add_u64 v[30:31], s[10:11], 0, v[2:3]
	v_lshl_add_u64 v[32:33], s[12:13], 0, v[2:3]
	v_lshlrev_b32_e32 v2, 3, v4
	v_lshl_add_u64 v[2:3], s[8:9], 0, v[2:3]
	s_mov_b64 s[10:11], 0x5a00000
	v_ashrrev_i32_e32 v7, 31, v6
	v_lshl_add_u64 v[34:35], v[2:3], 0, s[10:11]
	v_lshl_add_u64 v[2:3], v[6:7], 2, s[8:9]
	s_mov_b64 s[10:11], 0x1c3000
	v_lshl_add_u64 v[36:37], v[2:3], 0, s[10:11]
	v_lshlrev_b64 v[2:3], 12, v[6:7]
	v_lshlrev_b32_e32 v1, 2, v1
	v_cmp_eq_u32_e64 s[0:1], 0, v4
	v_lshl_add_u64 v[10:11], s[14:15], 0, v[8:9]
	v_lshl_add_u64 v[14:15], s[12:13], 0, v[8:9]
	v_lshl_add_u64 v[38:39], s[8:9], 0, v[2:3]
	v_lshl_add_u64 v[40:41], s[6:7], 0, v[2:3]
	s_mov_b64 s[6:7], 0
	s_branch .LBB0_1727

.LBB0_1727:
	s_waitcnt lgkmcnt(0)
	v_lshl_add_u64 v[56:57], v[38:39], 0, v[8:9]
	v_lshl_add_u64 v[60:61], v[40:41], 0, v[8:9]
	v_add_u32_e32 v50, 0x4000, v6
	v_ashrrev_i32_e32 v51, 31, v50
	v_lshlrev_b64 v[62:63], 11, v[50:51]
	v_lshl_add_u64 v[62:63], v[34:35], 0, v[62:63]
	s_mov_b32 s85, 0
	s_mov_b32 s84, 0x400000
	v_lshl_add_u64 v[58:59], v[56:57], 0, s[84:85]
	v_lshl_add_u64 v[60:61], v[60:61], 0, s[84:85]
	s_mov_b32 s84, 0xda00000
	v_lshl_add_u64 v[100:101], v[56:57], 0, s[84:85]
	s_add_u32 s84, s84, 0x400000
	v_lshl_add_u64 v[102:103], v[56:57], 0, s[84:85]
	s_add_u32 s84, s84, 0x400000
	v_lshl_add_u64 v[104:105], v[56:57], 0, s[84:85]
	s_add_u32 s84, s84, 0x400000
	v_lshl_add_u64 v[106:107], v[56:57], 0, s[84:85]
	s_add_u32 s84, s84, 0x400000
	v_lshl_add_u64 v[108:109], v[56:57], 0, s[84:85]
	s_add_u32 s84, s84, 0x400000
	v_lshl_add_u64 v[110:111], v[56:57], 0, s[84:85]
	s_add_u32 s84, s84, 0x400000
	v_lshl_add_u64 v[112:113], v[56:57], 0, s[84:85]
	s_add_u32 s84, s84, 0x400000
	v_lshl_add_u64 v[114:115], v[56:57], 0, s[84:85]
	s_add_u32 s84, s84, 0x400000
	v_lshl_add_u64 v[116:117], v[56:57], 0, s[84:85]
	s_add_u32 s84, s84, 0x400000
	v_lshl_add_u64 v[118:119], v[56:57], 0, s[84:85]
	s_add_u32 s84, s84, 0x400000
	v_lshl_add_u64 v[120:121], v[56:57], 0, s[84:85]
	global_load_dwordx4 v[148:151], v[100:101], off
	global_load_dwordx4 v[152:155], v[102:103], off
	global_load_dwordx4 v[156:159], v[104:105], off
	global_load_dwordx4 v[160:163], v[106:107], off
	global_load_dwordx4 v[164:167], v[108:109], off
	global_load_dwordx4 v[168:171], v[110:111], off
	global_load_dwordx4 v[172:175], v[112:113], off
	global_load_dwordx4 v[176:179], v[114:115], off
	global_load_dwordx4 v[180:183], v[116:117], off
	global_load_dwordx4 v[184:187], v[118:119], off
	global_load_dwordx4 v[188:191], v[120:121], off
	global_load_dwordx4 v[92:95], v[60:61], off
	global_load_dwordx4 v[42:45], v[10:11], off
	global_load_dwordx4 v[122:125], v[12:13], off
	global_load_dwordx4 v[130:133], v[14:15], off
	global_load_dwordx4 v[192:195], v[100:101], off offset:1024
	global_load_dwordx4 v[196:199], v[102:103], off offset:1024
	global_load_dwordx4 v[200:203], v[104:105], off offset:1024
	global_load_dwordx4 v[204:207], v[106:107], off offset:1024
	global_load_dwordx4 v[208:211], v[108:109], off offset:1024
	global_load_dwordx4 v[212:215], v[110:111], off offset:1024
	global_load_dwordx4 v[216:219], v[112:113], off offset:1024
	global_load_dwordx4 v[220:223], v[114:115], off offset:1024
	global_load_dwordx4 v[80:83], v[116:117], off offset:1024
	global_load_dwordx4 v[84:87], v[118:119], off offset:1024
	global_load_dwordx4 v[88:91], v[120:121], off offset:1024
	global_load_dwordx4 v[96:99], v[60:61], off offset:1024
	global_load_dwordx4 v[46:49], v[10:11], off offset:1024
	global_load_dwordx4 v[126:129], v[12:13], off offset:1024
	global_load_dwordx4 v[134:137], v[14:15], off offset:1024
	s_waitcnt vmcnt(15)
	v_pk_add_f32 v[66:67], v[150:151], 0 op_sel_hi:[1,0]
	v_pk_add_f32 v[64:65], v[148:149], 0 op_sel_hi:[1,0]
	v_pk_add_f32 v[66:67], v[66:67], v[154:155]
	v_pk_add_f32 v[64:65], v[64:65], v[152:153]
	v_pk_add_f32 v[66:67], v[66:67], v[158:159]
	v_pk_add_f32 v[64:65], v[64:65], v[156:157]
	v_pk_add_f32 v[66:67], v[66:67], v[162:163]
	v_pk_add_f32 v[64:65], v[64:65], v[160:161]
	v_pk_add_f32 v[66:67], v[66:67], v[166:167]
	v_pk_add_f32 v[64:65], v[64:65], v[164:165]
	v_pk_add_f32 v[66:67], v[66:67], v[170:171]
	v_pk_add_f32 v[64:65], v[64:65], v[168:169]
	v_pk_add_f32 v[66:67], v[66:67], v[174:175]
	v_pk_add_f32 v[64:65], v[64:65], v[172:173]
	v_pk_add_f32 v[66:67], v[66:67], v[178:179]
	v_pk_add_f32 v[64:65], v[64:65], v[176:177]
	v_pk_add_f32 v[66:67], v[66:67], v[182:183]
	v_pk_add_f32 v[64:65], v[64:65], v[180:181]
	v_pk_add_f32 v[66:67], v[66:67], v[186:187]
	v_pk_add_f32 v[64:65], v[64:65], v[184:185]
	v_pk_add_f32 v[66:67], v[66:67], v[190:191]
	v_pk_add_f32 v[64:65], v[64:65], v[188:189]
	v_pk_mul_f32 v[44:45], v[44:45], 0.5 op_sel_hi:[1,0]
	v_pk_mul_f32 v[42:43], v[42:43], 0.5 op_sel_hi:[1,0]
	v_pk_fma_f32 v[4:5], v[66:67], v[44:45], v[94:95]
	v_pk_fma_f32 v[2:3], v[64:65], v[42:43], v[92:93]
	v_mul_f32_e32 v138, v5, v5
	v_mul_f32_e32 v7, v3, v3
	global_store_dwordx4 v[58:59], v[2:5], off
	v_fmac_f32_e32 v7, v2, v2
	v_fmac_f32_e32 v138, v4, v4
	v_add_f32_e32 v7, v7, v138
	v_pk_add_f32 v[132:133], v[132:133], 1.0 op_sel_hi:[1,0]
	v_pk_add_f32 v[130:131], v[130:131], 1.0 op_sel_hi:[1,0]
	v_pk_mul_f32 v[124:125], v[124:125], v[132:133]
	v_pk_mul_f32 v[122:123], v[122:123], v[130:131]
	v_pk_mul_f32 v[142:143], v[4:5], v[124:125]
	v_pk_mul_f32 v[140:141], v[2:3], v[122:123]
	s_nop 0
	v_cvt_pk_bf16_f32 v140, v140, v141
	v_cvt_pk_bf16_f32 v141, v142, v143
	global_store_dwordx2 v[62:63], v[140:141], off
	s_waitcnt vmcnt(2)
	v_pk_add_f32 v[66:67], v[194:195], 0 op_sel_hi:[1,0]
	v_pk_add_f32 v[64:65], v[192:193], 0 op_sel_hi:[1,0]
	v_pk_add_f32 v[66:67], v[66:67], v[198:199]
	v_pk_add_f32 v[64:65], v[64:65], v[196:197]
	v_pk_add_f32 v[66:67], v[66:67], v[202:203]
	v_pk_add_f32 v[64:65], v[64:65], v[200:201]
	v_pk_add_f32 v[66:67], v[66:67], v[206:207]
	v_pk_add_f32 v[64:65], v[64:65], v[204:205]
	v_pk_add_f32 v[66:67], v[66:67], v[210:211]
	v_pk_add_f32 v[64:65], v[64:65], v[208:209]
	v_pk_add_f32 v[66:67], v[66:67], v[214:215]
	v_pk_add_f32 v[64:65], v[64:65], v[212:213]
	v_pk_add_f32 v[66:67], v[66:67], v[218:219]
	v_pk_add_f32 v[64:65], v[64:65], v[216:217]
	v_pk_add_f32 v[66:67], v[66:67], v[222:223]
	v_pk_add_f32 v[64:65], v[64:65], v[220:221]
	v_pk_add_f32 v[66:67], v[66:67], v[82:83]
	v_pk_add_f32 v[64:65], v[64:65], v[80:81]
	v_pk_add_f32 v[66:67], v[66:67], v[86:87]
	v_pk_add_f32 v[64:65], v[64:65], v[84:85]
	v_pk_add_f32 v[66:67], v[66:67], v[90:91]
	v_pk_add_f32 v[64:65], v[64:65], v[88:89]
	v_pk_mul_f32 v[48:49], v[48:49], 0.5 op_sel_hi:[1,0]
	v_pk_mul_f32 v[46:47], v[46:47], 0.5 op_sel_hi:[1,0]
	v_pk_fma_f32 v[4:5], v[66:67], v[48:49], v[98:99]
	v_pk_fma_f32 v[2:3], v[64:65], v[46:47], v[96:97]
	v_mul_f32_e32 v139, v5, v5
	v_mul_f32_e32 v138, v3, v3
	v_fmac_f32_e32 v138, v2, v2
	v_fmac_f32_e32 v139, v4, v4
	global_store_dwordx4 v[58:59], v[2:5], off offset:1024
	v_add_f32_e32 v138, v138, v139
	v_add_f32_e32 v7, v7, v138
	v_pk_add_f32 v[136:137], v[136:137], 1.0 op_sel_hi:[1,0]
	v_pk_add_f32 v[134:135], v[134:135], 1.0 op_sel_hi:[1,0]
	v_pk_mul_f32 v[128:129], v[128:129], v[136:137]
	v_pk_mul_f32 v[126:127], v[126:127], v[134:135]
	v_pk_mul_f32 v[142:143], v[4:5], v[128:129]
	v_pk_mul_f32 v[140:141], v[2:3], v[126:127]
	s_nop 0
	v_cvt_pk_bf16_f32 v140, v140, v141
	v_cvt_pk_bf16_f32 v141, v142, v143
	global_store_dwordx2 v[62:63], v[140:141], off offset:512
	global_load_dwordx4 v[148:151], v[100:101], off offset:2048
	global_load_dwordx4 v[152:155], v[102:103], off offset:2048
	global_load_dwordx4 v[156:159], v[104:105], off offset:2048
	global_load_dwordx4 v[160:163], v[106:107], off offset:2048
	global_load_dwordx4 v[164:167], v[108:109], off offset:2048
	global_load_dwordx4 v[168:171], v[110:111], off offset:2048
	global_load_dwordx4 v[172:175], v[112:113], off offset:2048
	global_load_dwordx4 v[176:179], v[114:115], off offset:2048
	global_load_dwordx4 v[180:183], v[116:117], off offset:2048
	global_load_dwordx4 v[184:187], v[118:119], off offset:2048
	global_load_dwordx4 v[188:191], v[120:121], off offset:2048
	global_load_dwordx4 v[92:95], v[60:61], off offset:2048
	global_load_dwordx4 v[42:45], v[10:11], off offset:2048
	global_load_dwordx4 v[122:125], v[12:13], off offset:2048
	global_load_dwordx4 v[130:133], v[14:15], off offset:2048
	global_load_dwordx4 v[192:195], v[100:101], off offset:3072
	global_load_dwordx4 v[196:199], v[102:103], off offset:3072
	global_load_dwordx4 v[200:203], v[104:105], off offset:3072
	global_load_dwordx4 v[204:207], v[106:107], off offset:3072
	global_load_dwordx4 v[208:211], v[108:109], off offset:3072
	global_load_dwordx4 v[212:215], v[110:111], off offset:3072
	global_load_dwordx4 v[216:219], v[112:113], off offset:3072
	global_load_dwordx4 v[220:223], v[114:115], off offset:3072
	global_load_dwordx4 v[80:83], v[116:117], off offset:3072
	global_load_dwordx4 v[84:87], v[118:119], off offset:3072
	global_load_dwordx4 v[88:91], v[120:121], off offset:3072
	global_load_dwordx4 v[96:99], v[60:61], off offset:3072
	global_load_dwordx4 v[46:49], v[10:11], off offset:3072
	global_load_dwordx4 v[126:129], v[12:13], off offset:3072
	global_load_dwordx4 v[134:137], v[14:15], off offset:3072
	s_waitcnt vmcnt(15)
	v_pk_add_f32 v[66:67], v[150:151], 0 op_sel_hi:[1,0]
	v_pk_add_f32 v[64:65], v[148:149], 0 op_sel_hi:[1,0]
	v_pk_add_f32 v[66:67], v[66:67], v[154:155]
	v_pk_add_f32 v[64:65], v[64:65], v[152:153]
	v_pk_add_f32 v[66:67], v[66:67], v[158:159]
	v_pk_add_f32 v[64:65], v[64:65], v[156:157]
	v_pk_add_f32 v[66:67], v[66:67], v[162:163]
	v_pk_add_f32 v[64:65], v[64:65], v[160:161]
	v_pk_add_f32 v[66:67], v[66:67], v[166:167]
	v_pk_add_f32 v[64:65], v[64:65], v[164:165]
	v_pk_add_f32 v[66:67], v[66:67], v[170:171]
	v_pk_add_f32 v[64:65], v[64:65], v[168:169]
	v_pk_add_f32 v[66:67], v[66:67], v[174:175]
	v_pk_add_f32 v[64:65], v[64:65], v[172:173]
	v_pk_add_f32 v[66:67], v[66:67], v[178:179]
	v_pk_add_f32 v[64:65], v[64:65], v[176:177]
	v_pk_add_f32 v[66:67], v[66:67], v[182:183]
	v_pk_add_f32 v[64:65], v[64:65], v[180:181]
	v_pk_add_f32 v[66:67], v[66:67], v[186:187]
	v_pk_add_f32 v[64:65], v[64:65], v[184:185]
	v_pk_add_f32 v[66:67], v[66:67], v[190:191]
	v_pk_add_f32 v[64:65], v[64:65], v[188:189]
	v_pk_mul_f32 v[44:45], v[44:45], 0.5 op_sel_hi:[1,0]
	v_pk_mul_f32 v[42:43], v[42:43], 0.5 op_sel_hi:[1,0]
	v_pk_fma_f32 v[4:5], v[66:67], v[44:45], v[94:95]
	v_pk_fma_f32 v[2:3], v[64:65], v[42:43], v[92:93]
	v_mul_f32_e32 v139, v5, v5
	v_mul_f32_e32 v138, v3, v3
	v_fmac_f32_e32 v138, v2, v2
	v_fmac_f32_e32 v139, v4, v4
	global_store_dwordx4 v[58:59], v[2:5], off offset:2048
	v_add_f32_e32 v138, v138, v139
	v_add_f32_e32 v7, v7, v138
	v_pk_add_f32 v[132:133], v[132:133], 1.0 op_sel_hi:[1,0]
	v_pk_add_f32 v[130:131], v[130:131], 1.0 op_sel_hi:[1,0]
	v_pk_mul_f32 v[124:125], v[124:125], v[132:133]
	v_pk_mul_f32 v[122:123], v[122:123], v[130:131]
	v_pk_mul_f32 v[142:143], v[4:5], v[124:125]
	v_pk_mul_f32 v[140:141], v[2:3], v[122:123]
	s_nop 0
	v_cvt_pk_bf16_f32 v140, v140, v141
	v_cvt_pk_bf16_f32 v141, v142, v143
	global_store_dwordx2 v[62:63], v[140:141], off offset:1024
	s_waitcnt vmcnt(2)
	v_pk_add_f32 v[66:67], v[194:195], 0 op_sel_hi:[1,0]
	v_pk_add_f32 v[64:65], v[192:193], 0 op_sel_hi:[1,0]
	v_pk_add_f32 v[66:67], v[66:67], v[198:199]
	v_pk_add_f32 v[64:65], v[64:65], v[196:197]
	v_pk_add_f32 v[66:67], v[66:67], v[202:203]
	v_pk_add_f32 v[64:65], v[64:65], v[200:201]
	v_pk_add_f32 v[66:67], v[66:67], v[206:207]
	v_pk_add_f32 v[64:65], v[64:65], v[204:205]
	v_pk_add_f32 v[66:67], v[66:67], v[210:211]
	v_pk_add_f32 v[64:65], v[64:65], v[208:209]
	v_pk_add_f32 v[66:67], v[66:67], v[214:215]
	v_pk_add_f32 v[64:65], v[64:65], v[212:213]
	v_pk_add_f32 v[66:67], v[66:67], v[218:219]
	v_pk_add_f32 v[64:65], v[64:65], v[216:217]
	v_pk_add_f32 v[66:67], v[66:67], v[222:223]
	v_pk_add_f32 v[64:65], v[64:65], v[220:221]
	v_pk_add_f32 v[66:67], v[66:67], v[82:83]
	v_pk_add_f32 v[64:65], v[64:65], v[80:81]
	v_pk_add_f32 v[66:67], v[66:67], v[86:87]
	v_pk_add_f32 v[64:65], v[64:65], v[84:85]
	v_pk_add_f32 v[66:67], v[66:67], v[90:91]
	v_pk_add_f32 v[64:65], v[64:65], v[88:89]
	v_pk_mul_f32 v[48:49], v[48:49], 0.5 op_sel_hi:[1,0]
	v_pk_mul_f32 v[46:47], v[46:47], 0.5 op_sel_hi:[1,0]
	v_pk_fma_f32 v[4:5], v[66:67], v[48:49], v[98:99]
	v_pk_fma_f32 v[2:3], v[64:65], v[46:47], v[96:97]
	v_mul_f32_e32 v139, v5, v5
	v_mul_f32_e32 v138, v3, v3
	v_fmac_f32_e32 v138, v2, v2
	v_fmac_f32_e32 v139, v4, v4
	global_store_dwordx4 v[58:59], v[2:5], off offset:3072
	v_add_f32_e32 v138, v138, v139
	v_add_f32_e32 v7, v7, v138
	v_pk_add_f32 v[136:137], v[136:137], 1.0 op_sel_hi:[1,0]
	v_pk_add_f32 v[134:135], v[134:135], 1.0 op_sel_hi:[1,0]
	v_pk_mul_f32 v[128:129], v[128:129], v[136:137]
	v_pk_mul_f32 v[126:127], v[126:127], v[134:135]
	v_pk_mul_f32 v[142:143], v[4:5], v[128:129]
	v_pk_mul_f32 v[140:141], v[2:3], v[126:127]
	s_nop 0
	v_cvt_pk_bf16_f32 v140, v140, v141
	v_cvt_pk_bf16_f32 v141, v142, v143
	global_store_dwordx2 v[62:63], v[140:141], off offset:1536
	ds_bpermute_b32 v2, v1, v7
	s_waitcnt lgkmcnt(0)
	v_add_f32_e32 v2, v7, v2
	ds_bpermute_b32 v3, v74, v2
	s_waitcnt lgkmcnt(0)
	v_add_f32_e32 v2, v2, v3
	ds_bpermute_b32 v3, v75, v2
	s_waitcnt lgkmcnt(0)
	v_add_f32_e32 v2, v2, v3
	ds_bpermute_b32 v3, v76, v2
	s_waitcnt lgkmcnt(0)
	v_add_f32_e32 v2, v2, v3
	ds_bpermute_b32 v3, v77, v2
	s_waitcnt lgkmcnt(0)
	v_add_f32_e32 v2, v2, v3
	ds_bpermute_b32 v3, v78, v2
	s_and_saveexec_b64 s[8:9], s[0:1]
	s_cbranch_execz .LBB0_1726
	s_waitcnt lgkmcnt(0)
	v_add_f32_e32 v2, v2, v3
	global_store_dword v[36:37], v2, off
	s_branch .LBB0_1726
